# conv/kvprep/qprep phase: pulled pair index mapped through a bijection that interleaves VALU-bound conv items with bandwidth-bound prep items (9+5+9 per round even layers, 9+10 odd); on top of v88
# speedup vs baseline: 1.0047x; 1.0047x over previous
.LBB0_227:
	s_or_b64 exec, exec, s[0:1]
	s_waitcnt lgkmcnt(0)
	s_barrier
	ds_read_b32 v1, v230
	s_waitcnt lgkmcnt(0)
	v_readfirstlane_b32 s40, v1
	s_lshr_b32 s41, s73, 1
	s_cmp_ge_u32 s40, s41
	s_cbranch_scc1 .Lcvmap_done
	s_cmpk_eq_u32 s41, 0xb80
	s_cbranch_scc0 .Lcvmap_odd
	s_mul_i32 s0, s40, 2850
	s_lshr_b32 s0, s0, 16
	s_mul_i32 s1, s0, 23
	s_sub_u32 s1, s40, s1
	s_cmp_lt_u32 s1, 23
	s_cbranch_scc1 .Lcvmap_e1
	s_sub_u32 s0, s0, 1
	s_add_u32 s1, s1, 23
.Lcvmap_e1:
	s_cmp_lt_u32 s1, 9
	s_cbranch_scc0 .Lcvmap_e2
	s_mul_i32 s0, s0, 9
	s_add_u32 s40, s0, s1
	s_branch .Lcvmap_set
.Lcvmap_e2:
	s_cmp_lt_u32 s1, 14
	s_cbranch_scc0 .Lcvmap_e3
	s_mul_i32 s0, s0, 5
	s_add_u32 s40, s0, s1
	s_addk_i32 s40, 1143
	s_branch .Lcvmap_set
.Lcvmap_e3:
	s_mul_i32 s0, s0, 9
	s_add_u32 s40, s0, s1
	s_addk_i32 s40, 1778
	s_branch .Lcvmap_set
.Lcvmap_odd:
	s_mul_i32 s0, s40, 3450
	s_lshr_b32 s0, s0, 16
	s_mul_i32 s1, s0, 19
	s_sub_u32 s1, s40, s1
	s_cmp_lt_u32 s1, 19
	s_cbranch_scc1 .Lcvmap_o1
	s_sub_u32 s0, s0, 1
	s_add_u32 s1, s1, 19

.Lcvmap_o2:
	s_mul_i32 s0, s0, 10
	s_add_u32 s40, s0, s1
	s_addk_i32 s40, 1143
.Lcvmap_set:
	v_mov_b32_e32 v1, s40
.Lcvmap_done:
	v_lshlrev_b32_e32 v2, 1, v1
	v_add_u32_e32 v0, v2, v216
	v_cmp_le_i32_e64 s[40:41], s73, v2
	v_max_i32_e32 v2, v2, v0
	v_cmp_gt_i32_e32 vcc, s73, v2
	s_and_saveexec_b64 s[66:67], vcc
	s_cbranch_execz .LBB0_222
	s_movk_i32 s0, 0x8ff
	v_cmp_lt_i32_e32 vcc, s0, v0
	s_and_saveexec_b64 s[0:1], vcc
	s_xor_b64 s[44:45], exec, s[0:1]
	s_cbranch_execz .LBB0_255
	v_cmp_le_i32_e32 vcc, s72, v0
	s_and_saveexec_b64 s[0:1], vcc
	s_xor_b64 s[0:1], exec, s[0:1]
	s_cbranch_execz .LBB0_233
	v_readlane_b32 s42, v254, 54
	v_mov_b32_e32 v5, v217
	s_nop 0
	v_add_u32_e32 v3, s42, v0
	v_lshlrev_b32_e32 v0, 4, v3
	v_readlane_b32 s42, v252, 19
	v_ashrrev_i32_e32 v2, 2, v5
	v_and_b32_e32 v0, 0xffffffc0, v0
	v_readlane_b32 s43, v252, 20
	v_lshlrev_b32_e32 v3, 8, v3
	v_add_u32_e32 v4, v2, v0
	v_mov_b64_e32 v[0:1], s[42:43]
	v_and_b32_e32 v16, 0x300, v3
	v_lshlrev_b32_e32 v3, 3, v5
	v_mad_i64_i32 v[0:1], s[42:43], v4, s33, v[0:1]
	v_and_b32_e32 v3, 24, v3
	v_lshl_add_u64 v[0:1], v[0:1], 0, v[16:17]
	v_lshlrev_b32_e32 v16, 1, v3
	v_lshl_add_u64 v[0:1], v[0:1], 0, v[16:17]
	s_mov_b64 s[42:43], 0xa922000
	v_lshl_add_u64 v[8:9], v[0:1], 0, s[42:43]
	s_mov_b32 s42, 0xa922000
	v_add_co_u32_e32 v0, vcc, s42, v0
	global_load_dwordx4 v[10:13], v[8:9], off offset:128
	global_load_dwordx4 v[18:21], v[8:9], off offset:192
	v_addc_co_u32_e32 v1, vcc, 0, v1, vcc
	global_load_dwordx4 v[22:25], v[0:1], off
	global_load_dwordx4 v[26:29], v[8:9], off offset:64
	v_cmp_lt_i32_e32 vcc, v226, v220
	s_waitcnt vmcnt(3)
	v_lshlrev_b32_e32 v16, 16, v13
	v_cndmask_b32_e32 v0, v218, v226, vcc
	v_lshlrev_b32_e32 v5, 2, v0
	v_lshlrev_b32_e32 v0, 2, v3
	global_load_dwordx4 v[30:33], v0, s[48:49] offset:16
	global_load_dwordx4 v[34:37], v0, s[48:49]
	global_load_dwordx4 v[38:41], v0, s[48:49] offset:144
	global_load_dwordx4 v[42:45], v0, s[48:49] offset:128
	global_load_dwordx4 v[46:49], v0, s[48:49] offset:272
	global_load_dwordx4 v[50:53], v0, s[48:49] offset:256
	global_load_dwordx4 v[54:57], v0, s[48:49] offset:400
	global_load_dwordx4 v[58:61], v0, s[48:49] offset:384
	s_waitcnt vmcnt(9)
	v_and_b32_e32 v1, 0xffff0000, v22
	v_lshlrev_b32_e32 v0, 16, v22
	v_and_b32_e32 v7, 0xffff0000, v13
	v_and_b32_e32 v65, 0xffff0000, v23
	v_lshlrev_b32_e32 v64, 16, v23
	v_and_b32_e32 v71, 0xffff0000, v18
	v_lshlrev_b32_e32 v70, 16, v18
	v_and_b32_e32 v75, 0xffff0000, v19
	v_lshlrev_b32_e32 v74, 16, v19
	v_and_b32_e32 v19, 0xffff0000, v12
	v_lshlrev_b32_e32 v18, 16, v12
	v_pk_mul_f32 v[12:13], v[0:1], v[0:1]
	v_pk_mul_f32 v[78:79], v[64:65], v[64:65]
	v_add_f32_e32 v6, v12, v13
	s_waitcnt vmcnt(8)
	v_and_b32_e32 v15, 0xffff0000, v26
	v_lshlrev_b32_e32 v14, 16, v26
	v_and_b32_e32 v23, 0xffff0000, v27
	v_lshlrev_b32_e32 v22, 16, v27
	v_and_b32_e32 v27, 0xffff0000, v24
	v_lshlrev_b32_e32 v26, 16, v24
	v_add_f32_e32 v6, v78, v6
	v_pk_mul_f32 v[82:83], v[26:27], v[26:27]
	v_add_f32_e32 v6, v79, v6
	v_and_b32_e32 v69, 0xffff0000, v25
	v_lshlrev_b32_e32 v68, 16, v25
	v_add_f32_e32 v6, v82, v6
	v_pk_mul_f32 v[88:89], v[68:69], v[68:69]
	v_add_f32_e32 v6, v83, v6
	v_add_f32_e32 v6, v88, v6
	v_and_b32_e32 v63, 0xffff0000, v21
	v_lshlrev_b32_e32 v62, 16, v21
	v_and_b32_e32 v77, 0xffff0000, v20
	v_lshlrev_b32_e32 v76, 16, v20
	v_pk_mul_f32 v[20:21], v[14:15], v[14:15]
	v_add_f32_e32 v6, v89, v6
	v_add_f32_e32 v6, v20, v6
	v_pk_mul_f32 v[80:81], v[22:23], v[22:23]
	v_add_f32_e32 v6, v21, v6
	v_and_b32_e32 v67, 0xffff0000, v28
	v_lshlrev_b32_e32 v66, 16, v28
	v_add_f32_e32 v6, v80, v6
	v_pk_mul_f32 v[86:87], v[66:67], v[66:67]
	v_add_f32_e32 v6, v81, v6
	v_and_b32_e32 v25, 0xffff0000, v29
	v_lshlrev_b32_e32 v24, 16, v29
	v_add_f32_e32 v6, v86, v6
	v_pk_mul_f32 v[90:91], v[24:25], v[24:25]
	v_add_f32_e32 v6, v87, v6
	v_and_b32_e32 v29, 0xffff0000, v10
	v_lshlrev_b32_e32 v28, 16, v10
	v_add_f32_e32 v6, v90, v6
	v_pk_mul_f32 v[92:93], v[28:29], v[28:29]
	v_add_f32_e32 v6, v91, v6
	v_and_b32_e32 v73, 0xffff0000, v11
	v_lshlrev_b32_e32 v72, 16, v11
	v_add_f32_e32 v6, v92, v6
	v_pk_mul_f32 v[96:97], v[72:73], v[72:73]
	v_add_f32_e32 v6, v93, v6
	v_add_f32_e32 v6, v96, v6
	v_pk_mul_f32 v[100:101], v[18:19], v[18:19]
	v_add_f32_e32 v6, v97, v6
	v_add_f32_e32 v6, v100, v6
	v_add_f32_e32 v6, v101, v6
	v_fmac_f32_e32 v6, v16, v16
	v_pk_mul_f32 v[94:95], v[70:71], v[70:71]
	v_fmac_f32_e32 v6, v7, v7
	v_add_f32_e32 v6, v94, v6
	v_pk_mul_f32 v[98:99], v[74:75], v[74:75]
	v_add_f32_e32 v6, v95, v6
	v_add_f32_e32 v6, v98, v6
	v_pk_mul_f32 v[102:103], v[76:77], v[76:77]
	v_add_f32_e32 v6, v99, v6
	v_add_f32_e32 v6, v102, v6
	v_pk_mul_f32 v[10:11], v[62:63], v[62:63]
	v_add_f32_e32 v6, v103, v6
	v_add_f32_e32 v6, v10, v6
	v_add_f32_e32 v6, v11, v6
	ds_bpermute_b32 v5, v5, v6
	v_cmp_lt_i32_e32 vcc, v225, v220
	s_waitcnt lgkmcnt(0)
	v_add_f32_e32 v5, v6, v5
	v_cndmask_b32_e32 v10, v218, v225, vcc
	v_lshlrev_b32_e32 v10, 2, v10
	ds_bpermute_b32 v6, v10, v5
	s_waitcnt lgkmcnt(0)
	v_add_f32_e32 v5, v5, v6
	v_fmamk_f32 v5, v5, 0x3c000000, v231
	v_mul_f32_e32 v6, 0x4b800000, v5
	v_cmp_gt_f32_e32 vcc, s3, v5
	s_nop 1
	v_cndmask_b32_e32 v5, v5, v6, vcc
	v_rsq_f32_e32 v5, v5
	s_nop 0
	v_mul_f32_e32 v6, 0x45800000, v5
	v_cndmask_b32_e32 v6, v5, v6, vcc
	s_waitcnt vmcnt(7)
	v_pk_mul_f32 v[20:21], v[30:31], v[6:7] op_sel_hi:[1,0]
	s_waitcnt vmcnt(6)
	v_pk_mul_f32 v[10:11], v[34:35], v[6:7] op_sel_hi:[1,0]
	s_waitcnt vmcnt(4)
	v_pk_mul_f32 v[34:35], v[42:43], v[6:7] op_sel_hi:[1,0]
	v_pk_mul_f32 v[42:43], v[44:45], v[6:7] op_sel_hi:[1,0]
	v_pk_mul_f32 v[44:45], v[38:39], v[6:7] op_sel_hi:[1,0]
	v_pk_mul_f32 v[38:39], v[20:21], v[26:27]
	v_pk_mul_f32 v[20:21], v[40:41], v[6:7] op_sel_hi:[1,0]
	v_pk_mul_f32 v[12:13], v[36:37], v[6:7] op_sel_hi:[1,0]
	v_pk_mul_f32 v[26:27], v[20:21], v[24:25]
	s_waitcnt vmcnt(2)
	v_pk_mul_f32 v[20:21], v[50:51], v[6:7] op_sel_hi:[1,0]
	v_pk_mul_f32 v[30:31], v[32:33], v[6:7] op_sel_hi:[1,0]
	v_pk_mul_f32 v[32:33], v[12:13], v[64:65]
	v_pk_mul_f32 v[12:13], v[42:43], v[22:23]
	v_pk_mul_f32 v[42:43], v[20:21], v[28:29]
	v_pk_mul_f32 v[20:21], v[52:53], v[6:7] op_sel_hi:[1,0]
	v_mul_f32_e32 v5, v48, v6
	v_pk_mul_f32 v[40:41], v[20:21], v[72:73]
	v_pk_mul_f32 v[20:21], v[46:47], v[6:7] op_sel_hi:[1,0]
	s_waitcnt vmcnt(1)
	v_mov_b32_e32 v48, v57
	v_pk_mul_f32 v[36:37], v[30:31], v[68:69]
	v_pk_mul_f32 v[46:47], v[20:21], v[18:19]
	v_mul_f32_e32 v24, v5, v16
	s_waitcnt vmcnt(0)
	v_pk_mul_f32 v[18:19], v[58:59], v[6:7] op_sel_hi:[1,0]
	v_pk_mul_f32 v[20:21], v[60:61], v[6:7] op_sel_hi:[1,0]
	v_pk_mul_f32 v[22:23], v[54:55], v[6:7] op_sel_hi:[1,0]
	v_mul_f32_e32 v5, v56, v6
	v_pk_mul_f32 v[30:31], v[48:49], v[6:7] op_sel_hi:[1,0]
	v_mov_b32_e32 v6, v63
	v_pk_mul_f32 v[0:1], v[10:11], v[0:1]
	v_pk_mul_f32 v[10:11], v[34:35], v[14:15]
	v_pk_mul_f32 v[14:15], v[44:45], v[66:67]
	v_pk_mul_f32 v[18:19], v[18:19], v[70:71]
	v_pk_mul_f32 v[20:21], v[20:21], v[74:75]
	v_pk_mul_f32 v[22:23], v[22:23], v[76:77]
	v_mul_f32_e32 v28, v5, v62
	v_pk_mul_f32 v[30:31], v[30:31], v[6:7]
	v_cmp_lt_i32_e32 vcc, s2, v4
	s_and_saveexec_b64 s[42:43], vcc
	s_cbranch_execz .LBB0_232
	v_lshrrev_b32_e32 v4, 1, v4
	v_lshlrev_b32_e32 v2, 5, v2
	s_movk_i32 s76, 0x7e0
	v_and_or_b32 v4, v4, s76, v3
	v_readlane_b32 s68, v252, 63
	v_and_or_b32 v2, v2, s76, v3
	v_lshlrev_b32_e32 v16, 2, v4
	v_readlane_b32 s69, v253, 0
	v_lshlrev_b32_e32 v44, 2, v2
	v_mov_b32_e32 v45, v17
	v_lshl_add_u64 v[4:5], s[68:69], 0, v[16:17]
	s_mov_b64 s[70:71], 0x2000
	v_lshl_add_u64 v[68:69], s[68:69], 0, v[44:45]
	v_lshl_add_u64 v[6:7], v[4:5], 0, s[70:71]
	v_lshl_add_u64 v[72:73], v[68:69], 0, s[70:71]
	s_movk_i32 s70, 0x2000
	v_add_co_u32_e32 v2, vcc, s70, v4
	global_load_dwordx4 v[52:55], v16, s[68:69] offset:16
	global_load_dwordx4 v[48:51], v16, s[68:69]
	v_addc_co_u32_e32 v3, vcc, 0, v5, vcc
	global_load_dwordx4 v[56:59], v[2:3], off
	global_load_dwordx4 v[60:63], v[6:7], off offset:16
	v_add_co_u32_e32 v4, vcc, s70, v68
	v_mov_b32_e32 v29, v30
	s_nop 0
	v_addc_co_u32_e32 v5, vcc, 0, v69, vcc
	v_mov_b32_e32 v25, v31
	s_mov_b64 s[96:97], 0x2000
	s_waitcnt vmcnt(1)
	v_pk_mul_f32 v[2:3], v[10:11], v[56:57]
	s_nop 0
	v_pk_fma_f32 v[34:35], v[0:1], v[48:49], v[2:3] neg_lo:[0,0,1] neg_hi:[0,0,1]
	v_pk_mul_f32 v[0:1], v[0:1], v[56:57]
	s_nop 0
	v_pk_fma_f32 v[10:11], v[10:11], v[48:49], v[0:1]
	global_load_dwordx4 v[0:3], v44, s[68:69] offset:16
	global_load_dwordx4 v[64:67], v44, s[68:69]
	global_load_dwordx4 v[68:71], v[4:5], off
	s_nop 0
	global_load_dwordx4 v[4:7], v[72:73], off offset:16
	s_waitcnt vmcnt(1)
	v_pk_mul_f32 v[44:45], v[18:19], v[68:69]
	s_nop 0
	v_pk_fma_f32 v[48:49], v[42:43], v[64:65], v[44:45] neg_lo:[0,0,1] neg_hi:[0,0,1]
	v_pk_mul_f32 v[42:43], v[42:43], v[68:69]
	s_nop 0
	v_pk_fma_f32 v[18:19], v[18:19], v[64:65], v[42:43]
	v_pk_mul_f32 v[42:43], v[12:13], v[58:59]
	s_nop 0
	v_pk_fma_f32 v[42:43], v[32:33], v[50:51], v[42:43] neg_lo:[0,0,1] neg_hi:[0,0,1]
	v_pk_mul_f32 v[32:33], v[32:33], v[58:59]
	s_nop 0
	v_pk_fma_f32 v[12:13], v[12:13], v[50:51], v[32:33]
	v_pk_mul_f32 v[32:33], v[20:21], v[70:71]
	s_nop 0
	v_pk_fma_f32 v[50:51], v[40:41], v[66:67], v[32:33] neg_lo:[0,0,1] neg_hi:[0,0,1]
	v_pk_mul_f32 v[32:33], v[40:41], v[70:71]
	s_nop 0
	v_pk_fma_f32 v[20:21], v[20:21], v[66:67], v[32:33]
	v_pk_mul_f32 v[32:33], v[14:15], v[60:61]
	s_nop 0
	v_pk_fma_f32 v[40:41], v[38:39], v[52:53], v[32:33] neg_lo:[0,0,1] neg_hi:[0,0,1]
	v_pk_mul_f32 v[32:33], v[38:39], v[60:61]
	v_mov_b32_e32 v38, v40
	v_pk_fma_f32 v[14:15], v[14:15], v[52:53], v[32:33]
	s_waitcnt vmcnt(0)
	v_pk_mul_f32 v[32:33], v[22:23], v[4:5]
	v_pk_mul_f32 v[4:5], v[46:47], v[4:5]
	v_pk_fma_f32 v[44:45], v[46:47], v[0:1], v[32:33] neg_lo:[0,0,1] neg_hi:[0,0,1]
	v_pk_fma_f32 v[22:23], v[22:23], v[0:1], v[4:5]
	v_pk_mul_f32 v[0:1], v[26:27], v[62:63]
	v_mul_f32_e32 v32, v24, v6
	v_pk_fma_f32 v[4:5], v[36:37], v[54:55], v[0:1] neg_lo:[0,0,1] neg_hi:[0,0,1]
	v_pk_mul_f32 v[0:1], v[36:37], v[62:63]
	v_mov_b32_e32 v39, v41
	v_pk_fma_f32 v[26:27], v[26:27], v[54:55], v[0:1]
	v_mul_f32_e32 v0, v28, v2
	v_pk_mul_f32 v[28:29], v[28:29], v[6:7]
	v_mov_b32_e32 v6, v3
	v_pk_fma_f32 v[24:25], v[24:25], v[2:3], v[28:29] neg_lo:[0,0,1] neg_hi:[0,0,1]
	v_pk_mul_f32 v[2:3], v[30:31], v[6:7]
	v_mov_b32_e32 v36, v4
	v_mov_b32_e32 v1, v2
	v_mov_b32_e32 v33, v3
	v_pk_add_f32 v[28:29], v[0:1], v[32:33]
	v_mov_b32_e32 v0, v34
	v_mov_b32_e32 v1, v35
	v_mov_b32_e32 v32, v42
	v_mov_b32_e32 v33, v43
	v_mov_b32_e32 v37, v5
	v_mov_b32_e32 v42, v48
	v_mov_b32_e32 v43, v49
	v_mov_b32_e32 v40, v50
	v_mov_b32_e32 v41, v51
	v_mov_b32_e32 v46, v44
	v_mov_b32_e32 v47, v45
	v_mov_b32_e32 v31, v25
	v_mov_b32_e32 v30, v29
